# A-mixer attention loop unrolled 2x with ping-pong score registers: removes 32 v_cndmask copies per tile
# speedup vs baseline: 1.0240x; 1.0240x over previous
; template <int KIND> DI void attn_unit(const Params& P, int b, int h, int qb, char* shm, float lam, bool dry = false) {
;     ...
;         ATT_FIX(pb0, pb1, ATT_TILE(i + 1));
;         float rm, rm2;
;         if (NDB == 4) {
;             LDV(11); PVM(8); rm = max3f(pb0[0], pb0[1], pb1[0]); rm2 = max3f(pb0[2], pb0[3], pb1[1]); PIN(rm); PIN(rm2); SBAR();
;             LDV(12); PVM(9); rm = max3f(rm, pb1[2], pb1[3]); rm2 = max3f(rm2, pb0[4], pb0[5]); PIN(rm); PIN(rm2); SBAR();
;             LDV(13); PVM(10); rm = max3f(rm, pb0[6], pb0[7]); rm2 = max3f(rm2, pb1[4], pb1[5]); PIN(rm); PIN(rm2); SBAR();
;             LDV(14); PVM(11); rm = max3f(rm, pb1[6], pb1[7]); rm2 = max3f(rm2, pb0[8], pb0[9]); PIN(rm); PIN(rm2); SBAR();
;             LDV(15); PVM(12); rm = max3f(rm, pb0[10], pb0[11]); rm2 = max3f(rm2, pb1[8], pb1[9]); PIN(rm); PIN(rm2); SBAR();
;             PVM(13); rm = max3f(rm, pb1[10], pb1[11]); rm2 = max3f(rm2, pb0[12], pb0[13]); PIN(rm); PIN(rm2); SBAR();
;             PVM(14); rm = max3f(rm, pb0[14], pb0[15]); rm2 = max3f(rm2, pb1[12], pb1[13]); PIN(rm); PIN(rm2); SBAR();
;             PVM(15); rm = max3f(rm, pb1[14], pb1[15]); PIN(rm); SBAR();
;         } else {
;             LDV(7); PVM(4); rm = max3f(pb0[0], pb0[1], pb1[0]); rm2 = max3f(pb0[2], pb0[3], pb1[1]); rm = max3f(rm, pb1[2], pb1[3]); rm2 = max3f(rm2, pb0[4], pb0[5]); PIN(rm); PIN(rm2); SBAR();
;             PVM(5); rm = max3f(rm, pb0[6], pb0[7]); rm2 = max3f(rm2, pb1[4], pb1[5]); rm = max3f(rm, pb1[6], pb1[7]); rm2 = max3f(rm2, pb0[8], pb0[9]); PIN(rm); PIN(rm2); SBAR();
;             PVM(6); rm = max3f(rm, pb0[10], pb0[11]); rm2 = max3f(rm2, pb1[8], pb1[9]); rm = max3f(rm, pb1[10], pb1[11]); rm2 = max3f(rm2, pb0[12], pb0[13]); PIN(rm); PIN(rm2); SBAR();
;             PVM(7); rm = max3f(rm, pb0[14], pb0[15]); rm2 = max3f(rm2, pb1[12], pb1[13]); rm = max3f(rm, pb1[14], pb1[15]); PIN(rm); PIN(rm2); SBAR();
;         }
;     ...
;         rm = swapmax(max3f(rm, rm2, rm2));
;         if (KIND == 2) {
;             const u32x2 kx = *(const LAS u32x2*)(shm3 + sc + 32768);
;             const float xk0 = __uint_as_float(kx.x << 16) + __uint_as_float(kx.x & 0xffff0000u) + __uint_as_float(kx.y << 16);
;             const float ltot = swapsum(lsum);
;             const bool ok = (qkmax + cb + xk0) < (mhat + __builtin_amdgcn_logf(ltot) - 54.0f);
;             const bool allok = __all(ok) && !(ATT_TILE(i) > wt_hi);
.LBB0_405:
	s_waitcnt lgkmcnt(4)
	v_mfma_f32_32x32x16_bf16 v[68:83], v[172:175], v[164:167], v[68:83]
	s_cmp_lt_u32 s3, s7
	s_cbranch_scc1 .Lat1_nomask
	v_mov_b32_e32 v116, v245
	v_mov_b32_e32 v117, v245
	v_mov_b32_e32 v118, v245
	v_mov_b32_e32 v119, v245
	v_mov_b32_e32 v120, v245
	v_mov_b32_e32 v121, v245
	v_mov_b32_e32 v122, v245
	v_mov_b32_e32 v123, v245
	v_mov_b32_e32 v124, v245
	v_mov_b32_e32 v125, v245
	v_mov_b32_e32 v126, v245
	v_mov_b32_e32 v127, v245
	v_mov_b32_e32 v128, v245
	v_mov_b32_e32 v129, v245
	v_mov_b32_e32 v130, v245
	v_mov_b32_e32 v131, v245
	v_mov_b32_e32 v132, v245
	v_mov_b32_e32 v133, v245
	v_mov_b32_e32 v134, v245
	v_mov_b32_e32 v135, v245
	v_mov_b32_e32 v136, v245
	v_mov_b32_e32 v137, v245
	v_mov_b32_e32 v138, v245
	v_mov_b32_e32 v139, v245
	v_mov_b32_e32 v140, v245
	v_mov_b32_e32 v141, v245
	v_mov_b32_e32 v142, v245
	v_mov_b32_e32 v143, v245
	v_mov_b32_e32 v144, v245
	v_mov_b32_e32 v145, v245
	v_mov_b32_e32 v146, v245
	v_mov_b32_e32 v147, v245
.Lat1_nomask:
	v_add_f32_e32 v197, v197, v100
	ds_read_b64_tr_b16 v[84:85], v190 offset:30720
	ds_read_b64_tr_b16 v[86:87], v190 offset:31232
	v_max3_f32 v100, v116, v117, v132
	v_max3_f32 v101, v118, v119, v133
	s_nop 0
	s_waitcnt lgkmcnt(4)
	v_mfma_f32_32x32x16_bf16 v[52:67], v[176:179], v[164:167], v[52:67]
	ds_read_b64_tr_b16 v[88:89], v190 offset:19456
	ds_read_b64_tr_b16 v[90:91], v190 offset:19968
	v_max3_f32 v100, v100, v134, v135
	v_max3_f32 v101, v101, v120, v121
	s_nop 0
	s_waitcnt lgkmcnt(4)
	v_mfma_f32_32x32x16_bf16 v[36:51], v[180:183], v[164:167], v[36:51]
	ds_read_b64_tr_b16 v[92:93], v190 offset:23552
	ds_read_b64_tr_b16 v[94:95], v190 offset:24064
	v_max3_f32 v100, v100, v122, v123
	v_max3_f32 v101, v101, v136, v137
	s_nop 0
	s_waitcnt lgkmcnt(4)
	v_mfma_f32_32x32x16_bf16 v[20:35], v[84:87], v[164:167], v[20:35]
	ds_read_b64_tr_b16 v[96:97], v190 offset:27648
	ds_read_b64_tr_b16 v[98:99], v190 offset:28160
	v_max3_f32 v100, v100, v138, v139
	v_max3_f32 v101, v101, v124, v125
	s_nop 0
	s_waitcnt lgkmcnt(4)
	v_mfma_f32_32x32x16_bf16 v[68:83], v[88:91], v[168:171], v[68:83]
	ds_read_b64_tr_b16 v[84:85], v190 offset:31744
	ds_read_b64_tr_b16 v[86:87], v190 offset:32256
	v_max3_f32 v100, v100, v126, v127
	v_max3_f32 v101, v101, v140, v141
	s_nop 0
	s_waitcnt lgkmcnt(4)
	v_mfma_f32_32x32x16_bf16 v[52:67], v[92:95], v[168:171], v[52:67]
	v_max3_f32 v100, v100, v142, v143
	v_max3_f32 v101, v101, v128, v129
	s_nop 0
	s_waitcnt lgkmcnt(2)
	v_mfma_f32_32x32x16_bf16 v[36:51], v[96:99], v[168:171], v[36:51]
	v_max3_f32 v100, v100, v130, v131
	v_max3_f32 v101, v101, v144, v145
	s_nop 0
	s_waitcnt lgkmcnt(0)
	v_mfma_f32_32x32x16_bf16 v[20:35], v[84:87], v[168:171], v[20:35]
	v_max3_f32 v100, v100, v146, v147
	s_nop 0
	s_nop 0
	v_max3_f32 v100, v100, v101, v101
	s_add_i32 s3, s3, 1
	v_mov_b32_e32 v101, v100
	s_cmp_ge_u32 s3, s18
	s_nop 0
	v_permlane32_swap_b32_e32 v100, v101
	s_cbranch_scc1 .LBB0_408
	v_max_f32_e32 v100, v100, v100
	v_max_f32_e32 v101, v101, v101
	v_max_f32_e32 v100, v100, v101
	v_cmp_lt_f32_e32 vcc, s88, v100
	s_cbranch_vccz .LBB0_408
	v_max_f32_e32 v100, v100, v100
	v_max_f32_e32 v101, 0, v100
	v_exp_f32_e64 v100, -v101
	v_sub_f32_e32 v131, v131, v101
	v_sub_f32_e32 v130, v130, v101
	v_sub_f32_e32 v129, v129, v101
	v_pk_mul_f32 v[82:83], v[82:83], v[100:101] op_sel_hi:[1,0]
	v_pk_mul_f32 v[80:81], v[80:81], v[100:101] op_sel_hi:[1,0]
	v_pk_mul_f32 v[78:79], v[78:79], v[100:101] op_sel_hi:[1,0]
	v_pk_mul_f32 v[76:77], v[76:77], v[100:101] op_sel_hi:[1,0]
	v_pk_mul_f32 v[74:75], v[74:75], v[100:101] op_sel_hi:[1,0]
	v_pk_mul_f32 v[72:73], v[72:73], v[100:101] op_sel_hi:[1,0]
	v_pk_mul_f32 v[70:71], v[70:71], v[100:101] op_sel_hi:[1,0]
	v_pk_mul_f32 v[68:69], v[68:69], v[100:101] op_sel_hi:[1,0]
	v_pk_mul_f32 v[66:67], v[66:67], v[100:101] op_sel_hi:[1,0]
	v_pk_mul_f32 v[64:65], v[64:65], v[100:101] op_sel_hi:[1,0]
	v_pk_mul_f32 v[62:63], v[62:63], v[100:101] op_sel_hi:[1,0]
	v_pk_mul_f32 v[60:61], v[60:61], v[100:101] op_sel_hi:[1,0]
	v_pk_mul_f32 v[58:59], v[58:59], v[100:101] op_sel_hi:[1,0]
	v_pk_mul_f32 v[56:57], v[56:57], v[100:101] op_sel_hi:[1,0]
	v_pk_mul_f32 v[54:55], v[54:55], v[100:101] op_sel_hi:[1,0]
	v_pk_mul_f32 v[52:53], v[52:53], v[100:101] op_sel_hi:[1,0]
	v_pk_mul_f32 v[50:51], v[50:51], v[100:101] op_sel_hi:[1,0]
	v_pk_mul_f32 v[48:49], v[48:49], v[100:101] op_sel_hi:[1,0]
	v_pk_mul_f32 v[46:47], v[46:47], v[100:101] op_sel_hi:[1,0]
	v_pk_mul_f32 v[44:45], v[44:45], v[100:101] op_sel_hi:[1,0]
	v_pk_mul_f32 v[42:43], v[42:43], v[100:101] op_sel_hi:[1,0]
	v_pk_mul_f32 v[40:41], v[40:41], v[100:101] op_sel_hi:[1,0]
	v_pk_mul_f32 v[38:39], v[38:39], v[100:101] op_sel_hi:[1,0]
	v_pk_mul_f32 v[36:37], v[36:37], v[100:101] op_sel_hi:[1,0]
	v_pk_mul_f32 v[34:35], v[34:35], v[100:101] op_sel_hi:[1,0]
	v_pk_mul_f32 v[32:33], v[32:33], v[100:101] op_sel_hi:[1,0]
	v_pk_mul_f32 v[30:31], v[30:31], v[100:101] op_sel_hi:[1,0]
	v_pk_mul_f32 v[28:29], v[28:29], v[100:101] op_sel_hi:[1,0]
	v_pk_mul_f32 v[26:27], v[26:27], v[100:101] op_sel_hi:[1,0]
	v_pk_mul_f32 v[24:25], v[24:25], v[100:101] op_sel_hi:[1,0]
	v_pk_mul_f32 v[22:23], v[22:23], v[100:101] op_sel_hi:[1,0]
	v_pk_mul_f32 v[20:21], v[20:21], v[100:101] op_sel_hi:[1,0]
	v_sub_f32_e32 v128, v128, v101
	v_sub_f32_e32 v127, v127, v101
	v_sub_f32_e32 v126, v126, v101
	v_sub_f32_e32 v125, v125, v101
	v_sub_f32_e32 v124, v124, v101
	v_sub_f32_e32 v123, v123, v101
	v_sub_f32_e32 v122, v122, v101
	v_sub_f32_e32 v121, v121, v101
	v_sub_f32_e32 v120, v120, v101
	v_sub_f32_e32 v119, v119, v101
	v_sub_f32_e32 v118, v118, v101
	v_sub_f32_e32 v117, v117, v101
	v_sub_f32_e32 v116, v116, v101
	v_sub_f32_e32 v147, v147, v101
	v_sub_f32_e32 v146, v146, v101
	v_sub_f32_e32 v145, v145, v101
	v_sub_f32_e32 v144, v144, v101
	v_sub_f32_e32 v143, v143, v101
	v_sub_f32_e32 v142, v142, v101
	v_sub_f32_e32 v141, v141, v101
	v_sub_f32_e32 v140, v140, v101
	v_sub_f32_e32 v139, v139, v101
	v_sub_f32_e32 v138, v138, v101
	v_sub_f32_e32 v137, v137, v101
	v_sub_f32_e32 v136, v136, v101
	v_sub_f32_e32 v135, v135, v101
	v_sub_f32_e32 v134, v134, v101
	v_sub_f32_e32 v133, v133, v101
	v_sub_f32_e32 v132, v132, v101
	v_sub_f32_e32 v19, v19, v101
	v_sub_f32_e32 v18, v18, v101
	v_sub_f32_e32 v17, v17, v101
	v_sub_f32_e32 v16, v16, v101
	v_sub_f32_e32 v15, v15, v101
	v_sub_f32_e32 v14, v14, v101
	v_sub_f32_e32 v13, v13, v101
	v_sub_f32_e32 v12, v12, v101
	v_sub_f32_e32 v11, v11, v101
	v_sub_f32_e32 v10, v10, v101
	v_sub_f32_e32 v9, v9, v101
	v_sub_f32_e32 v8, v8, v101
	v_sub_f32_e32 v7, v7, v101
	v_sub_f32_e32 v6, v6, v101
	v_sub_f32_e32 v5, v5, v101
	v_sub_f32_e32 v4, v4, v101
	v_mul_f32_e32 v197, v197, v100
.LBB0_408:
	s_add_i32 s1, s14, 0x8400
	s_cmp_lg_u32 s14, 0x18c00
	s_cselect_b32 s14, s1, 0
	s_add_i32 s4, s4, 64
	v_add_u32_e32 v192, 0x100, v192
	v_lshl_add_u64 v[184:185], v[184:185], 0, s[62:63]
	s_cmp_eq_u32 s3, s18
	v_lshl_add_u64 v[186:187], v[186:187], 0, s[92:93]
	s_cbranch_scc1 .LBB0_412
	s_mov_b32 s5, s0
	s_cmp_ge_u32 s3, s6
	s_mov_b64 s[0:1], -1
	s_cbranch_scc1 .Lat2_400
	s_branch .Lat2_411

; #define SBAR() __builtin_amdgcn_sched_barrier(0)
; template <int KIND> DI void attn_unit(const Params& P, int b, int h, int qb, char* shm, float lam, bool dry = false) {
;     ...
;     for (int i = 0; i < nt_eff; ++i) {
;         ATT_STEP_BAR(i);
;         const int sn = (sc == 3 * SLOT) ? 0 : sc + SLOT;
;         const lds_cptr vp = shm3 + sc + 16384 + vlane;
;         bf16x8 vq[4]; bf16x8 pw[4]; u32x4 w0, w1; float sacc = 0.f;
;     ...
;         ATT_KLD(sn, 0); ATT_XLD(sn);
;         SBAR();
;     ...
;         G1(pb0 = MF(kf[0], qr[0], negm), 0, w0, 0);  G1(pb1 = MF(kf[1], qr[0], negm), 2, w0, 1);
;         G1(pb0 = MF(kf[2], qr[1], pb0), 4, w0, 2);   G1(pb1 = MF(kf[3], qr[1], pb1), 6, w0, 3);
;         ATT_KLD(sn, 1);
;         SBAR();
;         G1(pb0 = MF(kf[0], qr[2], pb0), 8, w1, 0);   G1(pb1 = MF(kf[1], qr[2], pb1), 10, w1, 1);
;         LDV(0); SBAR();
;         G1(pb0 = MF(kf[2], qr[3], pb0), 12, w1, 2);
;         LDV(1); SBAR();
;         G1(pb1 = MF(kf[3], qr[3], pb1), 14, w1, 3);
;         LDV(2); SBAR();
;     ...
;         if (KIND == 2) { pb0 = MF(x0, ones, pb0); pb1 = MF(x1, ones, pb1); }
;         pw[0] = __builtin_bit_cast(bf16x8, w0); pw[1] = __builtin_bit_cast(bf16x8, w1);
;     ...
;         if (NDB == 4) {
;             LDV(3); PVM(0); E4(0, w0, 0); PIN(pa1); PIN(sacc); PIN(w0); SBAR();
;             LDV(4); PVM(1); E4(2, w0, 1); PIN(pa1); PIN(sacc); PIN(w0); SBAR();
;             LDV(5); PVM(2); E4(4, w0, 2); PIN(pa1); PIN(sacc); PIN(w0); SBAR();
;             LDV(6); PVM(3); E4(6, w0, 3); PIN(pa1); PIN(sacc); PIN(w0); SBAR();
;             LDV(7); PVM(4); E4(8, w1, 0); PIN(pa1); PIN(sacc); PIN(w1); SBAR();
;             LDV(8); PVM(5); E4(10, w1, 1); PIN(pa1); PIN(sacc); PIN(w1); SBAR();
;             LDV(9); PVM(6); E4(12, w1, 2); PIN(pa1); PIN(sacc); PIN(w1); SBAR();
;             LDV(10); PVM(7); E4(14, w1, 3); PIN(pa1); PIN(sacc); PIN(w1); SBAR();
;         } else {
;             LDV(3); PVM(0); E4(0, w0, 0); E4(2, w0, 1); PIN(pa1); PIN(sacc); PIN(w0); SBAR();
;             LDV(4); PVM(1); E4(4, w0, 2); E4(6, w0, 3); PIN(pa1); PIN(sacc); PIN(w0); SBAR();
;             LDV(5); PVM(2); E4(8, w1, 0); E4(10, w1, 1); PIN(pa1); PIN(sacc); PIN(w1); SBAR();
;             LDV(6); PVM(3); E4(12, w1, 2); E4(14, w1, 3); PIN(pa1); PIN(sacc); PIN(w1); SBAR();
;         }
;     ...
;         pw[2] = __builtin_bit_cast(bf16x8, w0); pw[3] = __builtin_bit_cast(bf16x8, w1);
;         lsum += sacc;
.Lat2_402:
	s_add_i32 s0, s11, s14
	s_mov_b32 s1, m0
	s_mov_b32 m0, s0
	s_nop 0
	global_load_lds_dwordx4 v[184:185], off
	s_mov_b32 m0, s1
	v_lshl_add_u64 v[100:101], v[184:185], 0, s[94:95]
	s_add_i32 s0, s15, s14
	s_mov_b32 s1, m0
	s_mov_b32 m0, s0
	s_nop 0
	global_load_lds_dwordx4 v[100:101], off
	s_mov_b32 m0, s1
	s_add_i32 s0, s16, s14
	s_mov_b32 s1, m0
	s_mov_b32 m0, s0
	s_nop 0
	global_load_lds_dwordx4 v[186:187], off
	s_mov_b32 m0, s1
	v_lshl_add_u64 v[100:101], v[186:187], 0, s[94:95]
	s_add_i32 s0, s17, s14
	s_mov_b32 s1, m0
	s_mov_b32 m0, s0
	s_nop 0
	global_load_lds_dwordx4 v[100:101], off
	s_mov_b32 m0, s1
.Lat2_403:
	s_add_i32 s0, s5, 0x8400
	s_cmp_lg_u32 s5, 0x18c00
	s_cselect_b32 s0, s0, 0
	v_add_u32_e32 v168, s0, v193
	ds_read_b128 v[84:87], v168
	ds_read_b128 v[172:175], v168 offset:512
	ds_read_b128 v[176:179], v168 offset:2048
	ds_read_b128 v[180:183], v168 offset:2560
	v_add_u32_e32 v190, s5, v196
	s_waitcnt lgkmcnt(3)
	v_mfma_f32_32x32x16_bf16 v[100:115], v[84:87], v[160:163], v[4:19]
	v_exp_f32_e32 v116, v116
	v_exp_f32_e32 v117, v117
	v_add_f32_e32 v84, 0, v116
	v_add_f32_e32 v191, v117, v84
	v_cvt_pk_bf16_f32 v164, v116, v117
	s_waitcnt lgkmcnt(2)
	v_mfma_f32_32x32x16_bf16 v[84:99], v[172:175], v[160:163], v[4:19]
	v_exp_f32_e32 v118, v118
	v_exp_f32_e32 v119, v119
	v_add_f32_e32 v165, v191, v118
	v_add_f32_e32 v172, v119, v165
	v_cvt_pk_bf16_f32 v165, v118, v119
	s_waitcnt lgkmcnt(1)
	v_mfma_f32_32x32x16_bf16 v[100:115], v[176:179], v[156:159], v[100:115]
	v_exp_f32_e32 v120, v120
	v_exp_f32_e32 v121, v121
	v_add_f32_e32 v166, v172, v120
	v_add_f32_e32 v172, v121, v166
	v_cvt_pk_bf16_f32 v166, v120, v121
	s_waitcnt lgkmcnt(0)
	v_mfma_f32_32x32x16_bf16 v[84:99], v[180:183], v[156:159], v[84:99]
	v_exp_f32_e32 v122, v122
	v_exp_f32_e32 v123, v123
	v_add_f32_e32 v167, v172, v122
	v_add_f32_e32 v191, v123, v167
	v_cvt_pk_bf16_f32 v167, v122, v123
	ds_read_b128 v[172:175], v168 offset:4096
	ds_read_b128 v[176:179], v168 offset:4608
	ds_read_b128 v[180:183], v168 offset:6144
	ds_read_b128 v[214:217], v168 offset:6656
	s_waitcnt lgkmcnt(3)
	v_mfma_f32_32x32x16_bf16 v[100:115], v[172:175], v[152:155], v[100:115]
	v_exp_f32_e32 v124, v124
	v_exp_f32_e32 v125, v125
	v_add_f32_e32 v168, v191, v124
	v_add_f32_e32 v172, v125, v168
	v_cvt_pk_bf16_f32 v168, v124, v125
	s_waitcnt lgkmcnt(2)
	v_mfma_f32_32x32x16_bf16 v[84:99], v[176:179], v[152:155], v[84:99]
	v_exp_f32_e32 v126, v126
	v_exp_f32_e32 v127, v127
	v_add_f32_e32 v169, v172, v126
	v_add_f32_e32 v176, v127, v169
	v_cvt_pk_bf16_f32 v169, v126, v127
	ds_read_b64_tr_b16 v[172:173], v190 offset:16384
	ds_read_b64_tr_b16 v[174:175], v190 offset:16896
	s_waitcnt lgkmcnt(3)
	v_mfma_f32_32x32x16_bf16 v[100:115], v[180:183], v[148:151], v[100:115]
	v_exp_f32_e32 v128, v128
	v_exp_f32_e32 v129, v129
	v_add_f32_e32 v170, v176, v128
	v_add_f32_e32 v180, v129, v170
	v_cvt_pk_bf16_f32 v170, v128, v129
	ds_read_b64_tr_b16 v[176:177], v190 offset:20480
	ds_read_b64_tr_b16 v[178:179], v190 offset:20992
	s_waitcnt lgkmcnt(4)
	v_mfma_f32_32x32x16_bf16 v[84:99], v[214:217], v[148:151], v[84:99]
	v_exp_f32_e32 v130, v130
	v_exp_f32_e32 v131, v131
	v_add_f32_e32 v171, v180, v130
	v_add_f32_e32 v180, v131, v171
	v_cvt_pk_bf16_f32 v171, v130, v131
	ds_read_b64_tr_b16 v[116:117], v190 offset:24576
	ds_read_b64_tr_b16 v[118:119], v190 offset:25088
	s_waitcnt lgkmcnt(4)
	v_mfma_f32_32x32x16_bf16 v[68:83], v[172:175], v[164:167], v[68:83]
	v_exp_f32_e32 v132, v132
	v_exp_f32_e32 v133, v133
	ds_read_b64_tr_b16 v[120:121], v190 offset:28672
	ds_read_b64_tr_b16 v[122:123], v190 offset:29184
	v_add_f32_e32 v124, v132, v180
	v_add_f32_e32 v180, v133, v124
	v_cvt_pk_bf16_f32 v128, v132, v133
	v_mov_b64_e32 v[124:125], v[164:165]
	v_mov_b64_e32 v[126:127], v[166:167]
	v_mov_b32_e32 v124, v128
	s_waitcnt lgkmcnt(4)
	v_mfma_f32_32x32x16_bf16 v[52:67], v[176:179], v[164:167], v[52:67]
	v_exp_f32_e32 v134, v134
	ds_read_b64_tr_b16 v[128:129], v190 offset:17408
	ds_read_b64_tr_b16 v[130:131], v190 offset:17920
	v_exp_f32_e32 v135, v135
	v_add_f32_e32 v125, v180, v134
	v_add_f32_e32 v172, v135, v125
	v_cvt_pk_bf16_f32 v125, v134, v135
	s_waitcnt lgkmcnt(4)
	v_mfma_f32_32x32x16_bf16 v[36:51], v[116:119], v[164:167], v[36:51]
	v_exp_f32_e32 v136, v136
	ds_read_b64_tr_b16 v[176:177], v190 offset:21504
	ds_read_b64_tr_b16 v[178:179], v190 offset:22016
	v_exp_f32_e32 v137, v137
	v_add_f32_e32 v116, v172, v136
	v_add_f32_e32 v172, v137, v116
	v_cvt_pk_bf16_f32 v126, v136, v137
	s_waitcnt lgkmcnt(4)
	v_mfma_f32_32x32x16_bf16 v[20:35], v[120:123], v[164:167], v[20:35]
	v_exp_f32_e32 v138, v138
	v_exp_f32_e32 v139, v139
	ds_read_b64_tr_b16 v[116:117], v190 offset:25600
	ds_read_b64_tr_b16 v[118:119], v190 offset:26112
	v_add_f32_e32 v120, v172, v138
	v_cvt_pk_bf16_f32 v127, v138, v139
	v_mov_b64_e32 v[166:167], v[126:127]
	v_add_f32_e32 v172, v139, v120
	v_mov_b64_e32 v[164:165], v[124:125]
	s_waitcnt lgkmcnt(4)
	v_mfma_f32_32x32x16_bf16 v[68:83], v[128:131], v[168:171], v[68:83]
	v_exp_f32_e32 v140, v140
	v_exp_f32_e32 v141, v141
	ds_read_b64_tr_b16 v[120:121], v190 offset:29696
	ds_read_b64_tr_b16 v[122:123], v190 offset:30208
	v_add_f32_e32 v124, v172, v140
	v_add_f32_e32 v180, v141, v124
	v_cvt_pk_bf16_f32 v128, v140, v141
	v_mov_b64_e32 v[124:125], v[168:169]
	v_mov_b64_e32 v[126:127], v[170:171]
	v_mov_b32_e32 v124, v128
	s_waitcnt lgkmcnt(4)
	v_mfma_f32_32x32x16_bf16 v[52:67], v[176:179], v[168:171], v[52:67]
	v_exp_f32_e32 v142, v142
	ds_read_b64_tr_b16 v[172:173], v190 offset:18432
	ds_read_b64_tr_b16 v[174:175], v190 offset:18944
	v_exp_f32_e32 v143, v143
	v_add_f32_e32 v125, v180, v142
	v_add_f32_e32 v128, v143, v125
	v_cvt_pk_bf16_f32 v125, v142, v143
	s_waitcnt lgkmcnt(4)
	v_mfma_f32_32x32x16_bf16 v[36:51], v[116:119], v[168:171], v[36:51]
	v_exp_f32_e32 v144, v144
	ds_read_b64_tr_b16 v[176:177], v190 offset:22528
	ds_read_b64_tr_b16 v[178:179], v190 offset:23040
	v_exp_f32_e32 v145, v145
	v_add_f32_e32 v116, v128, v144
	v_add_f32_e32 v116, v145, v116
	v_cvt_pk_bf16_f32 v126, v144, v145
	s_waitcnt lgkmcnt(4)
	v_mfma_f32_32x32x16_bf16 v[20:35], v[120:123], v[168:171], v[20:35]
	v_exp_f32_e32 v146, v146
	v_exp_f32_e32 v147, v147
	ds_read_b64_tr_b16 v[180:181], v190 offset:26624
	ds_read_b64_tr_b16 v[182:183], v190 offset:27136
	v_add_f32_e32 v116, v116, v146
	v_cvt_pk_bf16_f32 v127, v146, v147
	v_mov_b64_e32 v[170:171], v[126:127]
	v_add_f32_e32 v116, v147, v116
	v_mov_b64_e32 v[168:169], v[124:125]
	s_cmp_le_i32 s4, s13
	s_cbranch_scc1 .Lat2_405
; DI float max3f(float a, float b, float c) { float r; asm("v_max3_f32 %0, %1, %2, %3" : "=v"(r) : "v"(a), "v"(b), "v"(c)); return r; }
; #define SBAR() __builtin_amdgcn_sched_barrier(0)
; #define PIN(x) asm volatile("" : "+v"(x))
; #define LDV(j_) do { if ((j_) < 4 * NDB) { const lds_cptr a_ = vp + ((j_) % NDB) * 4096 + ((j_) / NDB) * 1024; const s16x4 lo_ = vtr(a_), hi_ = vtr(a_ + 512); \
;             vq[(j_) & 3] = (bf16x8){lo_[0], lo_[1], lo_[2], lo_[3], hi_[0], hi_[1], hi_[2], hi_[3]}; } } while (0)
; #define PVM(j_) o[(j_) % NDB] = MF(vq[(j_) & 3], pw[(j_) / NDB], o[(j_) % NDB])
; template <int KIND> DI void attn_unit(const Params& P, int b, int h, int qb, char* shm, float lam, bool dry = false) {
;     ...
;             LDV(11); PVM(8); rm = max3f(pb0[0], pb0[1], pb1[0]); rm2 = max3f(pb0[2], pb0[3], pb1[1]); PIN(rm); PIN(rm2); SBAR();
	ds_read2_b32 v[132:133], v192 offset1:1
	ds_read2_b32 v[134:135], v192 offset0:2 offset1:3
	ds_read2_b32 v[136:137], v192 offset0:8 offset1:9
	ds_read2_b32 v[138:139], v192 offset0:10 offset1:11
	ds_read2_b32 v[140:141], v192 offset0:16 offset1:17
	ds_read2_b32 v[142:143], v192 offset0:18 offset1:19
	ds_read2_b32 v[144:145], v192 offset0:24 offset1:25
	ds_read2_b32 v[146:147], v192 offset0:26 offset1:27
	ds_read2_b32 v[118:119], v192 offset0:32 offset1:33
	ds_read2_b32 v[120:121], v192 offset0:34 offset1:35
	ds_read2_b32 v[122:123], v192 offset0:40 offset1:41
	ds_read2_b32 v[124:125], v192 offset0:42 offset1:43
	s_waitcnt lgkmcnt(11)
	v_pk_add_f32 v[100:101], v[100:101], v[132:133]
	s_waitcnt lgkmcnt(5)
	v_pk_add_f32 v[112:113], v[112:113], v[144:145]
	v_pk_add_f32 v[110:111], v[110:111], v[142:143]
	v_pk_add_f32 v[108:109], v[108:109], v[140:141]
	ds_read2_b32 v[132:133], v192 offset0:48 offset1:49
	ds_read2_b32 v[140:141], v192 offset0:50 offset1:51
	ds_read2_b32 v[142:143], v192 offset0:56 offset1:57
	ds_read2_b32 v[144:145], v192 offset0:58 offset1:59
	s_waitcnt lgkmcnt(8)
	v_pk_add_f32 v[114:115], v[114:115], v[146:147]
	v_pk_add_f32 v[106:107], v[106:107], v[138:139]
	v_pk_add_f32 v[104:105], v[104:105], v[136:137]
	v_pk_add_f32 v[102:103], v[102:103], v[134:135]
	s_waitcnt lgkmcnt(7)
	v_pk_add_f32 v[84:85], v[84:85], v[118:119]
	s_waitcnt lgkmcnt(0)
	v_pk_add_f32 v[98:99], v[98:99], v[144:145]
	v_pk_add_f32 v[96:97], v[96:97], v[142:143]
	v_pk_add_f32 v[94:95], v[94:95], v[140:141]
	v_pk_add_f32 v[92:93], v[92:93], v[132:133]
	v_pk_add_f32 v[90:91], v[90:91], v[124:125]
	v_pk_add_f32 v[88:89], v[88:89], v[122:123]
	v_pk_add_f32 v[86:87], v[86:87], v[120:121]
.Lat2_405:
	s_waitcnt lgkmcnt(4)
	v_mfma_f32_32x32x16_bf16 v[68:83], v[172:175], v[164:167], v[68:83]
	s_cmp_lt_u32 s3, s7
	s_cbranch_scc1 .Lat2_nomask
	v_mov_b32_e32 v100, v245
	v_mov_b32_e32 v101, v245
	v_mov_b32_e32 v102, v245
	v_mov_b32_e32 v103, v245
	v_mov_b32_e32 v104, v245
	v_mov_b32_e32 v105, v245
	v_mov_b32_e32 v106, v245
	v_mov_b32_e32 v107, v245
	v_mov_b32_e32 v108, v245
	v_mov_b32_e32 v109, v245
	v_mov_b32_e32 v110, v245
	v_mov_b32_e32 v111, v245
	v_mov_b32_e32 v112, v245
	v_mov_b32_e32 v113, v245
	v_mov_b32_e32 v114, v245
	v_mov_b32_e32 v115, v245
	v_mov_b32_e32 v84, v245
	v_mov_b32_e32 v85, v245
	v_mov_b32_e32 v86, v245
	v_mov_b32_e32 v87, v245
	v_mov_b32_e32 v88, v245
	v_mov_b32_e32 v89, v245
	v_mov_b32_e32 v90, v245
	v_mov_b32_e32 v91, v245
	v_mov_b32_e32 v92, v245
	v_mov_b32_e32 v93, v245
	v_mov_b32_e32 v94, v245
	v_mov_b32_e32 v95, v245
	v_mov_b32_e32 v96, v245
	v_mov_b32_e32 v97, v245
	v_mov_b32_e32 v98, v245
	v_mov_b32_e32 v99, v245
; template <int KIND> DI void attn_unit(const Params& P, int b, int h, int qb, char* shm, float lam, bool dry = false) {
;     ...
;         if (NDB == 4) {
;             LDV(11); PVM(8); rm = max3f(pb0[0], pb0[1], pb1[0]); rm2 = max3f(pb0[2], pb0[3], pb1[1]); PIN(rm); PIN(rm2); SBAR();
;             LDV(12); PVM(9); rm = max3f(rm, pb1[2], pb1[3]); rm2 = max3f(rm2, pb0[4], pb0[5]); PIN(rm); PIN(rm2); SBAR();
;             LDV(13); PVM(10); rm = max3f(rm, pb0[6], pb0[7]); rm2 = max3f(rm2, pb1[4], pb1[5]); PIN(rm); PIN(rm2); SBAR();
;             LDV(14); PVM(11); rm = max3f(rm, pb1[6], pb1[7]); rm2 = max3f(rm2, pb0[8], pb0[9]); PIN(rm); PIN(rm2); SBAR();
;             LDV(15); PVM(12); rm = max3f(rm, pb0[10], pb0[11]); rm2 = max3f(rm2, pb1[8], pb1[9]); PIN(rm); PIN(rm2); SBAR();
;             PVM(13); rm = max3f(rm, pb1[10], pb1[11]); rm2 = max3f(rm2, pb0[12], pb0[13]); PIN(rm); PIN(rm2); SBAR();
;             PVM(14); rm = max3f(rm, pb0[14], pb0[15]); rm2 = max3f(rm2, pb1[12], pb1[13]); PIN(rm); PIN(rm2); SBAR();
;             PVM(15); rm = max3f(rm, pb1[14], pb1[15]); PIN(rm); SBAR();
;         } else {
;             LDV(7); PVM(4); rm = max3f(pb0[0], pb0[1], pb1[0]); rm2 = max3f(pb0[2], pb0[3], pb1[1]); rm = max3f(rm, pb1[2], pb1[3]); rm2 = max3f(rm2, pb0[4], pb0[5]); PIN(rm); PIN(rm2); SBAR();
;             PVM(5); rm = max3f(rm, pb0[6], pb0[7]); rm2 = max3f(rm2, pb1[4], pb1[5]); rm = max3f(rm, pb1[6], pb1[7]); rm2 = max3f(rm2, pb0[8], pb0[9]); PIN(rm); PIN(rm2); SBAR();
;             PVM(6); rm = max3f(rm, pb0[10], pb0[11]); rm2 = max3f(rm2, pb1[8], pb1[9]); rm = max3f(rm, pb1[10], pb1[11]); rm2 = max3f(rm2, pb0[12], pb0[13]); PIN(rm); PIN(rm2); SBAR();
;             PVM(7); rm = max3f(rm, pb0[14], pb0[15]); rm2 = max3f(rm2, pb1[12], pb1[13]); rm = max3f(rm, pb1[14], pb1[15]); PIN(rm); PIN(rm2); SBAR();
;         }
;     ...
;         rm = swapmax(max3f(rm, rm2, rm2));
;         if (KIND == 2) {
;             const u32x2 kx = *(const LAS u32x2*)(shm3 + sc + 32768);
;             const float xk0 = __uint_as_float(kx.x << 16) + __uint_as_float(kx.x & 0xffff0000u) + __uint_as_float(kx.y << 16);
;             const float ltot = swapsum(lsum);
;             const bool ok = (qkmax + cb + xk0) < (mhat + __builtin_amdgcn_logf(ltot) - 54.0f);
;             const bool allok = __all(ok) && !(ATT_TILE(i) > wt_hi);
;             if (lane == 0) vote[8 * (i & 3) + wid] = allok ? 1u : 0u;
.Lat2_nomask:
	v_add_f32_e32 v197, v197, v116
	ds_read_b64_tr_b16 v[132:133], v190 offset:30720
	ds_read_b64_tr_b16 v[134:135], v190 offset:31232
	v_max3_f32 v116, v100, v101, v84
	v_max3_f32 v117, v102, v103, v85
	s_nop 0
	s_waitcnt lgkmcnt(4)
	v_mfma_f32_32x32x16_bf16 v[52:67], v[176:179], v[164:167], v[52:67]
	ds_read_b64_tr_b16 v[136:137], v190 offset:19456
	ds_read_b64_tr_b16 v[138:139], v190 offset:19968
	v_max3_f32 v116, v116, v86, v87
	v_max3_f32 v117, v117, v104, v105
	s_nop 0
	s_waitcnt lgkmcnt(4)
	v_mfma_f32_32x32x16_bf16 v[36:51], v[180:183], v[164:167], v[36:51]
	ds_read_b64_tr_b16 v[140:141], v190 offset:23552
	ds_read_b64_tr_b16 v[142:143], v190 offset:24064
	v_max3_f32 v116, v116, v106, v107
	v_max3_f32 v117, v117, v88, v89
	s_nop 0
	s_waitcnt lgkmcnt(4)
	v_mfma_f32_32x32x16_bf16 v[20:35], v[132:135], v[164:167], v[20:35]
	ds_read_b64_tr_b16 v[144:145], v190 offset:27648
	ds_read_b64_tr_b16 v[146:147], v190 offset:28160
	v_max3_f32 v116, v116, v90, v91
	v_max3_f32 v117, v117, v108, v109
	s_nop 0
	s_waitcnt lgkmcnt(4)
	v_mfma_f32_32x32x16_bf16 v[68:83], v[136:139], v[168:171], v[68:83]
	ds_read_b64_tr_b16 v[132:133], v190 offset:31744
	ds_read_b64_tr_b16 v[134:135], v190 offset:32256
	v_max3_f32 v116, v116, v110, v111
	v_max3_f32 v117, v117, v92, v93
	s_nop 0
	s_waitcnt lgkmcnt(4)
	v_mfma_f32_32x32x16_bf16 v[52:67], v[140:143], v[168:171], v[52:67]
	v_max3_f32 v116, v116, v94, v95
	v_max3_f32 v117, v117, v112, v113
	s_nop 0
	s_waitcnt lgkmcnt(2)
	v_mfma_f32_32x32x16_bf16 v[36:51], v[144:147], v[168:171], v[36:51]
	v_max3_f32 v116, v116, v114, v115
	v_max3_f32 v117, v117, v96, v97
	s_nop 0
	s_waitcnt lgkmcnt(0)
	v_mfma_f32_32x32x16_bf16 v[20:35], v[132:135], v[168:171], v[20:35]
	v_max3_f32 v116, v116, v98, v99
	s_nop 0
	s_nop 0
	v_max3_f32 v116, v116, v117, v117
	s_add_i32 s3, s3, 1
	v_mov_b32_e32 v117, v116
	s_cmp_ge_u32 s3, s18
	s_nop 0
	v_permlane32_swap_b32_e32 v116, v117
	s_cbranch_scc1 .Lat2_408
	v_max_f32_e32 v116, v116, v116
	v_max_f32_e32 v117, v117, v117
	v_max_f32_e32 v116, v116, v117
	v_cmp_lt_f32_e32 vcc, s88, v116
	s_cbranch_vccz .Lat2_408
	v_max_f32_e32 v116, v116, v116
	v_max_f32_e32 v117, 0, v116
	v_exp_f32_e64 v116, -v117
	v_sub_f32_e32 v115, v115, v117
	v_sub_f32_e32 v114, v114, v117
	v_sub_f32_e32 v113, v113, v117
	v_pk_mul_f32 v[82:83], v[82:83], v[116:117] op_sel_hi:[1,0]
	v_pk_mul_f32 v[80:81], v[80:81], v[116:117] op_sel_hi:[1,0]
	v_pk_mul_f32 v[78:79], v[78:79], v[116:117] op_sel_hi:[1,0]
	v_pk_mul_f32 v[76:77], v[76:77], v[116:117] op_sel_hi:[1,0]
	v_pk_mul_f32 v[74:75], v[74:75], v[116:117] op_sel_hi:[1,0]
	v_pk_mul_f32 v[72:73], v[72:73], v[116:117] op_sel_hi:[1,0]
	v_pk_mul_f32 v[70:71], v[70:71], v[116:117] op_sel_hi:[1,0]
	v_pk_mul_f32 v[68:69], v[68:69], v[116:117] op_sel_hi:[1,0]
	v_pk_mul_f32 v[66:67], v[66:67], v[116:117] op_sel_hi:[1,0]
	v_pk_mul_f32 v[64:65], v[64:65], v[116:117] op_sel_hi:[1,0]
	v_pk_mul_f32 v[62:63], v[62:63], v[116:117] op_sel_hi:[1,0]
	v_pk_mul_f32 v[60:61], v[60:61], v[116:117] op_sel_hi:[1,0]
	v_pk_mul_f32 v[58:59], v[58:59], v[116:117] op_sel_hi:[1,0]
	v_pk_mul_f32 v[56:57], v[56:57], v[116:117] op_sel_hi:[1,0]
	v_pk_mul_f32 v[54:55], v[54:55], v[116:117] op_sel_hi:[1,0]
	v_pk_mul_f32 v[52:53], v[52:53], v[116:117] op_sel_hi:[1,0]
	v_pk_mul_f32 v[50:51], v[50:51], v[116:117] op_sel_hi:[1,0]
	v_pk_mul_f32 v[48:49], v[48:49], v[116:117] op_sel_hi:[1,0]
	v_pk_mul_f32 v[46:47], v[46:47], v[116:117] op_sel_hi:[1,0]
	v_pk_mul_f32 v[44:45], v[44:45], v[116:117] op_sel_hi:[1,0]
	v_pk_mul_f32 v[42:43], v[42:43], v[116:117] op_sel_hi:[1,0]
	v_pk_mul_f32 v[40:41], v[40:41], v[116:117] op_sel_hi:[1,0]
	v_pk_mul_f32 v[38:39], v[38:39], v[116:117] op_sel_hi:[1,0]
	v_pk_mul_f32 v[36:37], v[36:37], v[116:117] op_sel_hi:[1,0]
	v_pk_mul_f32 v[34:35], v[34:35], v[116:117] op_sel_hi:[1,0]
	v_pk_mul_f32 v[32:33], v[32:33], v[116:117] op_sel_hi:[1,0]
	v_pk_mul_f32 v[30:31], v[30:31], v[116:117] op_sel_hi:[1,0]
	v_pk_mul_f32 v[28:29], v[28:29], v[116:117] op_sel_hi:[1,0]
	v_pk_mul_f32 v[26:27], v[26:27], v[116:117] op_sel_hi:[1,0]
	v_pk_mul_f32 v[24:25], v[24:25], v[116:117] op_sel_hi:[1,0]
	v_pk_mul_f32 v[22:23], v[22:23], v[116:117] op_sel_hi:[1,0]
	v_pk_mul_f32 v[20:21], v[20:21], v[116:117] op_sel_hi:[1,0]
	v_sub_f32_e32 v112, v112, v117
	v_sub_f32_e32 v111, v111, v117
	v_sub_f32_e32 v110, v110, v117
	v_sub_f32_e32 v109, v109, v117
	v_sub_f32_e32 v108, v108, v117
	v_sub_f32_e32 v107, v107, v117
	v_sub_f32_e32 v106, v106, v117
	v_sub_f32_e32 v105, v105, v117
	v_sub_f32_e32 v104, v104, v117
	v_sub_f32_e32 v103, v103, v117
	v_sub_f32_e32 v102, v102, v117
	v_sub_f32_e32 v101, v101, v117
	v_sub_f32_e32 v100, v100, v117
	v_sub_f32_e32 v99, v99, v117
	v_sub_f32_e32 v98, v98, v117
	v_sub_f32_e32 v97, v97, v117
	v_sub_f32_e32 v96, v96, v117
	v_sub_f32_e32 v95, v95, v117
	v_sub_f32_e32 v94, v94, v117
	v_sub_f32_e32 v93, v93, v117
	v_sub_f32_e32 v92, v92, v117
	v_sub_f32_e32 v91, v91, v117
	v_sub_f32_e32 v90, v90, v117
	v_sub_f32_e32 v89, v89, v117
	v_sub_f32_e32 v88, v88, v117
	v_sub_f32_e32 v87, v87, v117
	v_sub_f32_e32 v86, v86, v117
	v_sub_f32_e32 v85, v85, v117
	v_sub_f32_e32 v84, v84, v117
	v_sub_f32_e32 v19, v19, v117
	v_sub_f32_e32 v18, v18, v117
	v_sub_f32_e32 v17, v17, v117
	v_sub_f32_e32 v16, v16, v117
	v_sub_f32_e32 v15, v15, v117
	v_sub_f32_e32 v14, v14, v117
	v_sub_f32_e32 v13, v13, v117
	v_sub_f32_e32 v12, v12, v117
	v_sub_f32_e32 v11, v11, v117
	v_sub_f32_e32 v10, v10, v117
	v_sub_f32_e32 v9, v9, v117
	v_sub_f32_e32 v8, v8, v117
	v_sub_f32_e32 v7, v7, v117
	v_sub_f32_e32 v6, v6, v117
	v_sub_f32_e32 v5, v5, v117
	v_sub_f32_e32 v4, v4, v117
	v_mul_f32_e32 v197, v197, v116

.LBB0_411:
	s_waitcnt vmcnt(4) lgkmcnt(0)
	s_barrier
	s_add_i32 s0, s3, 3
	s_cmp_ge_u32 s0, s18
	s_cbranch_scc0 .LBB0_402
	s_branch .LBB0_403
.Lat2_411:
	s_waitcnt vmcnt(4) lgkmcnt(0)
	s_barrier
	s_add_i32 s0, s3, 3
	s_cmp_ge_u32 s0, s18
	s_cbranch_scc0 .Lat2_402
	s_branch .Lat2_403
